# in-proj epilogue: bf16 store addresses = one base (computed under the load wait) + scalar row-block offset, replacing per-block 64-bit multiply and adds
# baseline (speedup 1.0000x reference)
.LBB0_513:
	s_or_b64 exec, exec, s[10:11]
	v_lshl_add_u64 v[146:147], v[218:219], 2, s[60:61]
	global_load_dword v48, v[146:147], off
	global_load_dword v160, v[146:147], off offset:64
	global_load_dword v168, v[146:147], off offset:128
	global_load_dword v167, v[146:147], off offset:192
	global_load_dword v166, v[146:147], off offset:512
	global_load_dword v165, v[146:147], off offset:576
	global_load_dword v164, v[146:147], off offset:640
	global_load_dword v163, v[146:147], off offset:704
	v_lshlrev_b64 v[156:157], 7, v[218:219]
	v_mad_i64_i32 v[220:221], s[10:11], v218, s21, 0
	v_lshl_add_u64 v[220:221], v[220:221], 1, s[4:5]
	v_ashrrev_i32_e32 v155, 31, v154
	v_lshl_add_u64 v[220:221], v[154:155], 1, v[220:221]
	s_waitcnt vmcnt(0)
	v_fmamk_f32 v48, v48, 0x3a800000, v234
	v_mul_f32_e32 v146, 0x4b800000, v48
	v_cmp_gt_f32_e32 vcc, s27, v48
	s_nop 1
	v_cndmask_b32_e32 v48, v48, v146, vcc
	v_rsq_f32_e32 v48, v48
	s_nop 0
	v_mul_f32_e32 v146, 0x45800000, v48
	v_cndmask_b32_e32 v158, v48, v146, vcc
	v_mov_b32_e32 v159, v158
	s_and_saveexec_b64 s[8:9], s[0:1]
	s_cbranch_execz .LBB0_519
	v_mov_b32_e32 v150, v158
	v_mov_b32_e32 v151, v158
	v_pk_fma_f32 v[148:149], v[128:129], v[150:151], v[144:145]
	v_pk_fma_f32 v[146:147], v[126:127], v[158:159], v[142:143]
	v_pk_fma_f32 v[152:153], v[124:125], v[150:151], v[140:141]
	v_pk_fma_f32 v[150:151], v[122:123], v[158:159], v[138:139]
	v_cmp_le_i32_e32 vcc, s21, v154
	s_and_saveexec_b64 s[10:11], vcc
	s_xor_b64 s[10:11], exec, s[10:11]
	s_cbranch_execz .LBB0_517
	s_andn2_b64 vcc, exec, s[68:69]
	s_cbranch_vccnz .LBB0_517
	v_lshl_add_u64 v[170:171], s[46:47], 0, v[156:157]
	v_subrev_u32_e32 v48, s21, v154
	v_lshl_add_u64 v[170:171], v[48:49], 2, v[170:171]
	global_store_dwordx4 v[170:171], v[146:149], off
	global_store_dwordx4 v[170:171], v[150:153], off offset:16
.LBB0_517:
	s_andn2_saveexec_b64 s[10:11], s[10:11]
	s_cbranch_execz .LBB0_519
	v_cvt_pk_bf16_f32 v146, v146, v147
	v_cvt_pk_bf16_f32 v147, v148, v149
	v_cvt_pk_bf16_f32 v148, v150, v151
	s_mul_i32 s98, s21, 0
	s_mov_b32 s99, 0
	v_lshl_add_u64 v[150:151], s[98:99], 0, v[220:221]
	v_cvt_pk_bf16_f32 v149, v152, v153
	global_store_dwordx4 v[150:151], v[146:149], off

.LBB0_523:
	s_andn2_saveexec_b64 s[8:9], s[8:9]
	s_cbranch_execz .LBB0_525
	v_cvt_pk_bf16_f32 v146, v146, v147
	v_cvt_pk_bf16_f32 v147, v148, v149
	v_cvt_pk_bf16_f32 v148, v150, v151
	s_mul_i32 s98, s21, 0
	s_mov_b32 s99, 0
	v_lshl_add_u64 v[150:151], s[98:99], 0, v[220:221]
	v_cvt_pk_bf16_f32 v149, v152, v153
	global_store_dwordx4 v[150:151], v[146:149], off offset:256

.LBB0_529:
	s_andn2_saveexec_b64 s[10:11], s[10:11]
	s_cbranch_execz .LBB0_531
	v_cvt_pk_bf16_f32 v146, v146, v147
	v_cvt_pk_bf16_f32 v147, v148, v149
	v_cvt_pk_bf16_f32 v148, v150, v151
	s_mul_i32 s98, s21, 32
	s_mov_b32 s99, 0
	v_lshl_add_u64 v[150:151], s[98:99], 0, v[220:221]
	v_cvt_pk_bf16_f32 v149, v152, v153
	global_store_dwordx4 v[150:151], v[146:149], off

.LBB0_535:
	s_andn2_saveexec_b64 s[8:9], s[8:9]
	s_cbranch_execz .LBB0_537
	v_cvt_pk_bf16_f32 v146, v146, v147
	v_cvt_pk_bf16_f32 v147, v148, v149
	v_cvt_pk_bf16_f32 v148, v150, v151
	s_mul_i32 s98, s21, 32
	s_mov_b32 s99, 0
	v_lshl_add_u64 v[150:151], s[98:99], 0, v[220:221]
	v_cvt_pk_bf16_f32 v149, v152, v153
	global_store_dwordx4 v[150:151], v[146:149], off offset:256

.LBB0_541:
	s_andn2_saveexec_b64 s[10:11], s[10:11]
	s_cbranch_execz .LBB0_543
	v_cvt_pk_bf16_f32 v146, v146, v147
	v_cvt_pk_bf16_f32 v147, v148, v149
	v_cvt_pk_bf16_f32 v148, v150, v151
	s_mul_i32 s98, s21, 64
	s_mov_b32 s99, 0
	v_lshl_add_u64 v[150:151], s[98:99], 0, v[220:221]
	v_cvt_pk_bf16_f32 v149, v152, v153
	global_store_dwordx4 v[150:151], v[146:149], off

.LBB0_547:
	s_andn2_saveexec_b64 s[8:9], s[8:9]
	s_cbranch_execz .LBB0_549
	v_cvt_pk_bf16_f32 v146, v146, v147
	v_cvt_pk_bf16_f32 v147, v148, v149
	v_cvt_pk_bf16_f32 v148, v150, v151
	s_mul_i32 s98, s21, 64
	s_mov_b32 s99, 0
	v_lshl_add_u64 v[150:151], s[98:99], 0, v[220:221]
	v_cvt_pk_bf16_f32 v149, v152, v153
	global_store_dwordx4 v[150:151], v[146:149], off offset:256

.LBB0_553:
	s_andn2_saveexec_b64 s[10:11], s[10:11]
	s_cbranch_execz .LBB0_555
	v_cvt_pk_bf16_f32 v146, v146, v147
	v_cvt_pk_bf16_f32 v147, v148, v149
	v_cvt_pk_bf16_f32 v148, v150, v151
	s_mul_i32 s98, s21, 96
	s_mov_b32 s99, 0
	v_lshl_add_u64 v[150:151], s[98:99], 0, v[220:221]
	v_cvt_pk_bf16_f32 v149, v152, v153
	global_store_dwordx4 v[150:151], v[146:149], off

.LBB0_559:
	s_andn2_saveexec_b64 s[8:9], s[8:9]
	s_cbranch_execz .LBB0_561
	v_cvt_pk_bf16_f32 v146, v146, v147
	v_cvt_pk_bf16_f32 v147, v148, v149
	v_cvt_pk_bf16_f32 v148, v150, v151
	s_mul_i32 s98, s21, 96
	s_mov_b32 s99, 0
	v_lshl_add_u64 v[150:151], s[98:99], 0, v[220:221]
	v_cvt_pk_bf16_f32 v149, v152, v153
	global_store_dwordx4 v[150:151], v[146:149], off offset:256

.LBB0_565:
	s_andn2_saveexec_b64 s[10:11], s[10:11]
	s_cbranch_execz .LBB0_567
	v_cvt_pk_bf16_f32 v146, v146, v147
	v_cvt_pk_bf16_f32 v147, v148, v149
	v_cvt_pk_bf16_f32 v148, v150, v151
	s_mul_i32 s98, s21, 256
	s_mov_b32 s99, 0
	v_lshl_add_u64 v[150:151], s[98:99], 0, v[220:221]
	v_cvt_pk_bf16_f32 v149, v152, v153
	global_store_dwordx4 v[150:151], v[146:149], off

.LBB0_571:
	s_andn2_saveexec_b64 s[8:9], s[8:9]
	s_cbranch_execz .LBB0_573
	v_cvt_pk_bf16_f32 v146, v146, v147
	v_cvt_pk_bf16_f32 v147, v148, v149
	v_cvt_pk_bf16_f32 v148, v150, v151
	s_mul_i32 s98, s21, 256
	s_mov_b32 s99, 0
	v_lshl_add_u64 v[150:151], s[98:99], 0, v[220:221]
	v_cvt_pk_bf16_f32 v149, v152, v153
	global_store_dwordx4 v[150:151], v[146:149], off offset:256

.LBB0_577:
	s_andn2_saveexec_b64 s[10:11], s[10:11]
	s_cbranch_execz .LBB0_579
	v_cvt_pk_bf16_f32 v146, v146, v147
	v_cvt_pk_bf16_f32 v147, v148, v149
	v_cvt_pk_bf16_f32 v148, v150, v151
	s_mul_i32 s98, s21, 288
	s_mov_b32 s99, 0
	v_lshl_add_u64 v[150:151], s[98:99], 0, v[220:221]
	v_cvt_pk_bf16_f32 v149, v152, v153
	global_store_dwordx4 v[150:151], v[146:149], off

.LBB0_583:
	s_andn2_saveexec_b64 s[8:9], s[8:9]
	s_cbranch_execz .LBB0_585
	v_cvt_pk_bf16_f32 v146, v146, v147
	v_cvt_pk_bf16_f32 v147, v148, v149
	v_cvt_pk_bf16_f32 v148, v150, v151
	s_mul_i32 s98, s21, 288
	s_mov_b32 s99, 0
	v_lshl_add_u64 v[150:151], s[98:99], 0, v[220:221]
	v_cvt_pk_bf16_f32 v149, v152, v153
	global_store_dwordx4 v[150:151], v[146:149], off offset:256

.LBB0_589:
	s_andn2_saveexec_b64 s[10:11], s[10:11]
	s_cbranch_execz .LBB0_591
	v_cvt_pk_bf16_f32 v146, v146, v147
	v_cvt_pk_bf16_f32 v147, v148, v149
	v_cvt_pk_bf16_f32 v148, v150, v151
	s_mul_i32 s98, s21, 320
	s_mov_b32 s99, 0
	v_lshl_add_u64 v[150:151], s[98:99], 0, v[220:221]
	v_cvt_pk_bf16_f32 v149, v152, v153
	global_store_dwordx4 v[150:151], v[146:149], off

.LBB0_595:
	s_andn2_saveexec_b64 s[8:9], s[8:9]
	s_cbranch_execz .LBB0_597
	v_cvt_pk_bf16_f32 v146, v146, v147
	v_cvt_pk_bf16_f32 v147, v148, v149
	v_cvt_pk_bf16_f32 v148, v150, v151
	s_mul_i32 s98, s21, 320
	s_mov_b32 s99, 0
	v_lshl_add_u64 v[150:151], s[98:99], 0, v[220:221]
	v_cvt_pk_bf16_f32 v149, v152, v153
	global_store_dwordx4 v[150:151], v[146:149], off offset:256
